# GEMM K-loops: back-edge SALU rotated above the loop barrier; LDS fragment reads issued before the DMA address/m0 set-up after each barrier
# speedup vs baseline: 1.0021x; 1.0021x over previous
.LBB0_289:
	ds_read_b128 v[148:151], v165
	ds_read_b128 v[152:155], v165 offset:1024
	ds_read_b128 v[156:159], v165 offset:2048
	ds_read_b128 v[168:171], v165 offset:3072
	ds_read_b128 v[172:175], v166
	ds_read_b128 v[176:179], v166 offset:1024
	ds_read_b128 v[180:183], v166 offset:2048
	ds_read_b128 v[184:187], v166 offset:3072
	s_add_u32 s54, s52, 0xfffc0080
	s_addc_u32 s55, s53, -1
	s_cmp_eq_u32 s85, 12
	s_cselect_b32 s57, s29, s55
	s_cselect_b32 s56, s81, s54
	s_cselect_b32 s55, s27, s84
	s_cselect_b32 s54, s82, s83
	v_lshl_add_u64 v[160:161], s[52:53], 0, v[140:141]
	s_add_i32 m0, s51, 0xc000
	ds_read_b128 v[188:191], v167
	ds_read_b128 v[192:195], v167 offset:1024
	ds_read_b128 v[200:203], v167 offset:2048
	ds_read_b128 v[204:207], v167 offset:3072
	ds_read_b128 v[208:211], v167 offset:4096
	ds_read_b128 v[212:215], v167 offset:5120
	ds_read_b128 v[216:219], v167 offset:6144
	ds_read_b128 v[220:223], v167 offset:7168
	global_load_lds_dwordx4 v[160:161], off
	v_lshl_add_u64 v[160:161], s[52:53], 0, v[142:143]
	s_add_i32 m0, s51, 0xe000
	s_nop 0
	global_load_lds_dwordx4 v[160:161], off
	s_waitcnt vmcnt(8)
	s_waitcnt lgkmcnt(0)
	s_barrier
	s_setprio 1
	s_waitcnt lgkmcnt(0)
	v_mfma_f32_16x16x32_bf16 v[126:129], v[148:151], v[188:191], v[126:129]
	v_mfma_f32_16x16x32_bf16 v[122:125], v[156:159], v[188:191], v[122:125]
	v_mfma_f32_16x16x32_bf16 v[110:113], v[148:151], v[200:203], v[110:113]
	v_mfma_f32_16x16x32_bf16 v[106:109], v[156:159], v[200:203], v[106:109]
	v_mfma_f32_16x16x32_bf16 v[94:97], v[148:151], v[208:211], v[94:97]
	v_mfma_f32_16x16x32_bf16 v[90:93], v[156:159], v[208:211], v[90:93]
	v_mfma_f32_16x16x32_bf16 v[78:81], v[148:151], v[216:219], v[78:81]
	v_mfma_f32_16x16x32_bf16 v[74:77], v[156:159], v[216:219], v[74:77]
	v_mfma_f32_16x16x32_bf16 v[126:129], v[152:155], v[192:195], v[126:129]
	v_mfma_f32_16x16x32_bf16 v[122:125], v[168:171], v[192:195], v[122:125]
	v_mfma_f32_16x16x32_bf16 v[110:113], v[152:155], v[204:207], v[110:113]
	v_mfma_f32_16x16x32_bf16 v[106:109], v[168:171], v[204:207], v[106:109]
	v_mfma_f32_16x16x32_bf16 v[94:97], v[152:155], v[212:215], v[94:97]
	v_mfma_f32_16x16x32_bf16 v[90:93], v[168:171], v[212:215], v[90:93]
	v_mfma_f32_16x16x32_bf16 v[78:81], v[152:155], v[220:223], v[78:81]
	v_mfma_f32_16x16x32_bf16 v[74:77], v[168:171], v[220:223], v[74:77]
	s_setprio 0
	s_setprio 1
	v_mfma_f32_16x16x32_bf16 v[118:121], v[172:175], v[188:191], v[118:121]
	v_mfma_f32_16x16x32_bf16 v[114:117], v[180:183], v[188:191], v[114:117]
	v_mfma_f32_16x16x32_bf16 v[102:105], v[172:175], v[200:203], v[102:105]
	v_mfma_f32_16x16x32_bf16 v[98:101], v[180:183], v[200:203], v[98:101]
	v_mfma_f32_16x16x32_bf16 v[86:89], v[172:175], v[208:211], v[86:89]
	v_mfma_f32_16x16x32_bf16 v[82:85], v[180:183], v[208:211], v[82:85]
	v_mfma_f32_16x16x32_bf16 v[70:73], v[172:175], v[216:219], v[70:73]
	v_mfma_f32_16x16x32_bf16 v[66:69], v[180:183], v[216:219], v[66:69]
	v_mfma_f32_16x16x32_bf16 v[118:121], v[176:179], v[192:195], v[118:121]
	v_mfma_f32_16x16x32_bf16 v[114:117], v[184:187], v[192:195], v[114:117]
	v_mfma_f32_16x16x32_bf16 v[102:105], v[176:179], v[204:207], v[102:105]
	v_mfma_f32_16x16x32_bf16 v[98:101], v[184:187], v[204:207], v[98:101]
	v_mfma_f32_16x16x32_bf16 v[86:89], v[176:179], v[212:215], v[86:89]
	v_mfma_f32_16x16x32_bf16 v[82:85], v[184:187], v[212:215], v[82:85]
	v_mfma_f32_16x16x32_bf16 v[70:73], v[176:179], v[220:223], v[70:73]
	v_mfma_f32_16x16x32_bf16 v[66:69], v[184:187], v[220:223], v[66:69]
	s_setprio 0
	s_barrier
	ds_read_b128 v[188:191], v167 offset:16384
	ds_read_b128 v[192:195], v167 offset:17408
	ds_read_b128 v[200:203], v167 offset:18432
	ds_read_b128 v[204:207], v167 offset:19456
	ds_read_b128 v[208:211], v167 offset:20480
	ds_read_b128 v[212:215], v167 offset:21504
	ds_read_b128 v[216:219], v167 offset:22528
	ds_read_b128 v[220:223], v167 offset:23552
	s_add_i32 s86, s74, s64
	s_mov_b32 m0, s86
	v_lshl_add_u64 v[160:161], s[54:55], 0, v[132:133]
	global_load_lds_dwordx4 v[160:161], off
	s_add_i32 m0, s86, 0x2000
	s_add_u32 s86, s54, 0x40000
	v_lshl_add_u64 v[196:197], s[54:55], 0, v[136:137]
	s_addc_u32 s87, s55, 0
	s_add_i32 s88, s75, s64
	global_load_lds_dwordx4 v[196:197], off
	v_lshl_add_u64 v[224:225], s[86:87], 0, v[132:133]
	s_mov_b32 m0, s88
	v_lshl_add_u64 v[226:227], s[56:57], 0, v[134:135]
	global_load_lds_dwordx4 v[224:225], off
	v_lshl_add_u64 v[224:225], s[86:87], 0, v[136:137]
	s_add_i32 m0, s88, 0x2000
	s_nop 0
	global_load_lds_dwordx4 v[224:225], off
	v_lshl_add_u64 v[224:225], s[56:57], 0, v[130:131]
	s_mov_b32 m0, s51
	s_nop 0
	global_load_lds_dwordx4 v[224:225], off
	s_mov_b32 m0, s65
	s_nop 0
	global_load_lds_dwordx4 v[226:227], off
	s_waitcnt vmcnt(8)
	s_waitcnt lgkmcnt(0)
	s_barrier
	s_setprio 1
	s_waitcnt lgkmcnt(0)
	v_mfma_f32_16x16x32_bf16 v[62:65], v[148:151], v[188:191], v[62:65]
	v_mfma_f32_16x16x32_bf16 v[58:61], v[156:159], v[188:191], v[58:61]
	v_mfma_f32_16x16x32_bf16 v[46:49], v[148:151], v[200:203], v[46:49]
	v_mfma_f32_16x16x32_bf16 v[42:45], v[156:159], v[200:203], v[42:45]
	v_mfma_f32_16x16x32_bf16 v[30:33], v[148:151], v[208:211], v[30:33]
	v_mfma_f32_16x16x32_bf16 v[26:29], v[156:159], v[208:211], v[26:29]
	v_mfma_f32_16x16x32_bf16 v[14:17], v[148:151], v[216:219], v[14:17]
	v_mfma_f32_16x16x32_bf16 v[10:13], v[156:159], v[216:219], v[10:13]
	v_mfma_f32_16x16x32_bf16 v[62:65], v[152:155], v[192:195], v[62:65]
	v_mfma_f32_16x16x32_bf16 v[58:61], v[168:171], v[192:195], v[58:61]
	v_mfma_f32_16x16x32_bf16 v[46:49], v[152:155], v[204:207], v[46:49]
	v_mfma_f32_16x16x32_bf16 v[42:45], v[168:171], v[204:207], v[42:45]
	v_mfma_f32_16x16x32_bf16 v[30:33], v[152:155], v[212:215], v[30:33]
	v_mfma_f32_16x16x32_bf16 v[26:29], v[168:171], v[212:215], v[26:29]
	v_mfma_f32_16x16x32_bf16 v[14:17], v[152:155], v[220:223], v[14:17]
	v_mfma_f32_16x16x32_bf16 v[10:13], v[168:171], v[220:223], v[10:13]
	s_setprio 0
	s_setprio 1
	v_mfma_f32_16x16x32_bf16 v[54:57], v[172:175], v[188:191], v[54:57]
	v_mfma_f32_16x16x32_bf16 v[50:53], v[180:183], v[188:191], v[50:53]
	v_mfma_f32_16x16x32_bf16 v[38:41], v[172:175], v[200:203], v[38:41]
	v_mfma_f32_16x16x32_bf16 v[34:37], v[180:183], v[200:203], v[34:37]
	v_mfma_f32_16x16x32_bf16 v[22:25], v[172:175], v[208:211], v[22:25]
	v_mfma_f32_16x16x32_bf16 v[18:21], v[180:183], v[208:211], v[18:21]
	v_mfma_f32_16x16x32_bf16 v[6:9], v[172:175], v[216:219], v[6:9]
	v_mfma_f32_16x16x32_bf16 v[2:5], v[180:183], v[216:219], v[2:5]
	v_mfma_f32_16x16x32_bf16 v[54:57], v[176:179], v[192:195], v[54:57]
	v_mfma_f32_16x16x32_bf16 v[50:53], v[184:187], v[192:195], v[50:53]
	v_mfma_f32_16x16x32_bf16 v[38:41], v[176:179], v[204:207], v[38:41]
	v_mfma_f32_16x16x32_bf16 v[34:37], v[184:187], v[204:207], v[34:37]
	v_mfma_f32_16x16x32_bf16 v[22:25], v[176:179], v[212:215], v[22:25]
	v_mfma_f32_16x16x32_bf16 v[18:21], v[184:187], v[212:215], v[18:21]
	v_mfma_f32_16x16x32_bf16 v[6:9], v[176:179], v[220:223], v[6:9]
	v_mfma_f32_16x16x32_bf16 v[2:5], v[184:187], v[220:223], v[2:5]
	s_setprio 0
	s_barrier
	s_add_i32 s86, 0, 0x18000
	v_add_u32_e32 v138, s86, v162
	s_add_i32 s87, 0, 0x1c000
	ds_read_b128 v[148:151], v138
	ds_read_b128 v[152:155], v138 offset:1024
	ds_read_b128 v[156:159], v138 offset:2048
	ds_read_b128 v[168:171], v138 offset:3072
	v_add_u32_e32 v138, s87, v162
	ds_read_b128 v[172:175], v138
	ds_read_b128 v[176:179], v138 offset:1024
	ds_read_b128 v[180:183], v138 offset:2048
	ds_read_b128 v[184:187], v138 offset:3072
	s_add_u32 s56, s56, 0x40000
	s_addc_u32 s57, s57, 0
	s_mov_b32 m0, s66
	v_lshl_add_u64 v[228:229], s[56:57], 0, v[130:131]
	ds_read_b128 v[188:191], v167 offset:32768
	ds_read_b128 v[192:195], v167 offset:33792
	ds_read_b128 v[200:203], v167 offset:34816
	ds_read_b128 v[204:207], v167 offset:35840
	ds_read_b128 v[208:211], v167 offset:36864
	ds_read_b128 v[212:215], v167 offset:37888
	ds_read_b128 v[216:219], v167 offset:38912
	ds_read_b128 v[220:223], v167 offset:39936
	global_load_lds_dwordx4 v[228:229], off
	v_lshl_add_u64 v[228:229], s[56:57], 0, v[134:135]
	s_mov_b32 m0, s67
	s_nop 0
	global_load_lds_dwordx4 v[228:229], off
	s_waitcnt vmcnt(8)
	s_waitcnt lgkmcnt(0)
	s_barrier
	s_setprio 1
	s_waitcnt lgkmcnt(0)
	v_mfma_f32_16x16x32_bf16 v[126:129], v[148:151], v[188:191], v[126:129]
	v_mfma_f32_16x16x32_bf16 v[122:125], v[156:159], v[188:191], v[122:125]
	v_mfma_f32_16x16x32_bf16 v[110:113], v[148:151], v[200:203], v[110:113]
	v_mfma_f32_16x16x32_bf16 v[106:109], v[156:159], v[200:203], v[106:109]
	v_mfma_f32_16x16x32_bf16 v[94:97], v[148:151], v[208:211], v[94:97]
	v_mfma_f32_16x16x32_bf16 v[90:93], v[156:159], v[208:211], v[90:93]
	v_mfma_f32_16x16x32_bf16 v[78:81], v[148:151], v[216:219], v[78:81]
	v_mfma_f32_16x16x32_bf16 v[74:77], v[156:159], v[216:219], v[74:77]
	v_mfma_f32_16x16x32_bf16 v[126:129], v[152:155], v[192:195], v[126:129]
	v_mfma_f32_16x16x32_bf16 v[122:125], v[168:171], v[192:195], v[122:125]
	v_mfma_f32_16x16x32_bf16 v[110:113], v[152:155], v[204:207], v[110:113]
	v_mfma_f32_16x16x32_bf16 v[106:109], v[168:171], v[204:207], v[106:109]
	v_mfma_f32_16x16x32_bf16 v[94:97], v[152:155], v[212:215], v[94:97]
	v_mfma_f32_16x16x32_bf16 v[90:93], v[168:171], v[212:215], v[90:93]
	v_mfma_f32_16x16x32_bf16 v[78:81], v[152:155], v[220:223], v[78:81]
	v_mfma_f32_16x16x32_bf16 v[74:77], v[168:171], v[220:223], v[74:77]
	s_setprio 0
	s_setprio 1
	v_mfma_f32_16x16x32_bf16 v[118:121], v[172:175], v[188:191], v[118:121]
	v_mfma_f32_16x16x32_bf16 v[114:117], v[180:183], v[188:191], v[114:117]
	v_mfma_f32_16x16x32_bf16 v[102:105], v[172:175], v[200:203], v[102:105]
	v_mfma_f32_16x16x32_bf16 v[98:101], v[180:183], v[200:203], v[98:101]
	v_mfma_f32_16x16x32_bf16 v[86:89], v[172:175], v[208:211], v[86:89]
	v_mfma_f32_16x16x32_bf16 v[82:85], v[180:183], v[208:211], v[82:85]
	v_mfma_f32_16x16x32_bf16 v[70:73], v[172:175], v[216:219], v[70:73]
	v_mfma_f32_16x16x32_bf16 v[66:69], v[180:183], v[216:219], v[66:69]
	v_mfma_f32_16x16x32_bf16 v[118:121], v[176:179], v[192:195], v[118:121]
	v_mfma_f32_16x16x32_bf16 v[114:117], v[184:187], v[192:195], v[114:117]
	v_mfma_f32_16x16x32_bf16 v[102:105], v[176:179], v[204:207], v[102:105]
	v_mfma_f32_16x16x32_bf16 v[98:101], v[184:187], v[204:207], v[98:101]
	v_mfma_f32_16x16x32_bf16 v[86:89], v[176:179], v[212:215], v[86:89]
	v_mfma_f32_16x16x32_bf16 v[82:85], v[184:187], v[212:215], v[82:85]
	v_mfma_f32_16x16x32_bf16 v[70:73], v[176:179], v[220:223], v[70:73]
	v_mfma_f32_16x16x32_bf16 v[66:69], v[184:187], v[220:223], v[66:69]
	s_setprio 0
	s_barrier
	ds_read_b128 v[188:191], v167 offset:49152
	ds_read_b128 v[192:195], v167 offset:50176
	ds_read_b128 v[200:203], v167 offset:51200
	ds_read_b128 v[204:207], v167 offset:52224
	ds_read_b128 v[208:211], v167 offset:53248
	ds_read_b128 v[212:215], v167 offset:54272
	ds_read_b128 v[216:219], v167 offset:55296
	ds_read_b128 v[220:223], v167 offset:56320
	s_add_i32 s56, s86, s64
	s_mov_b32 m0, s56
	v_lshl_add_u64 v[160:161], v[160:161], 0, s[14:15]
	global_load_lds_dwordx4 v[160:161], off
	s_add_i32 m0, s56, 0x2000
	s_add_u32 s54, s54, 0x40080
	v_lshl_add_u64 v[160:161], v[196:197], 0, s[14:15]
	s_addc_u32 s55, s55, 0
	s_add_i32 s56, s87, s64
	global_load_lds_dwordx4 v[160:161], off
	v_lshl_add_u64 v[160:161], s[54:55], 0, v[132:133]
	s_mov_b32 m0, s56
	s_nop 0
	global_load_lds_dwordx4 v[160:161], off
	v_lshl_add_u64 v[160:161], s[54:55], 0, v[136:137]
	s_add_i32 m0, s56, 0x2000
	s_nop 0
	global_load_lds_dwordx4 v[160:161], off
	v_lshl_add_u64 v[160:161], v[224:225], 0, s[14:15]
	s_mov_b32 m0, s68
	s_nop 0
	global_load_lds_dwordx4 v[160:161], off
	v_lshl_add_u64 v[160:161], v[226:227], 0, s[14:15]
	s_mov_b32 m0, s69
	s_nop 0
	global_load_lds_dwordx4 v[160:161], off
	s_waitcnt vmcnt(8)
	s_waitcnt lgkmcnt(0)
	s_barrier
	s_setprio 1
	s_waitcnt lgkmcnt(0)
	v_mfma_f32_16x16x32_bf16 v[62:65], v[148:151], v[188:191], v[62:65]
	v_mfma_f32_16x16x32_bf16 v[58:61], v[156:159], v[188:191], v[58:61]
	v_mfma_f32_16x16x32_bf16 v[46:49], v[148:151], v[200:203], v[46:49]
	v_mfma_f32_16x16x32_bf16 v[42:45], v[156:159], v[200:203], v[42:45]
	v_mfma_f32_16x16x32_bf16 v[30:33], v[148:151], v[208:211], v[30:33]
	v_mfma_f32_16x16x32_bf16 v[26:29], v[156:159], v[208:211], v[26:29]
	v_mfma_f32_16x16x32_bf16 v[14:17], v[148:151], v[216:219], v[14:17]
	v_mfma_f32_16x16x32_bf16 v[10:13], v[156:159], v[216:219], v[10:13]
	v_mfma_f32_16x16x32_bf16 v[62:65], v[152:155], v[192:195], v[62:65]
	v_mfma_f32_16x16x32_bf16 v[58:61], v[168:171], v[192:195], v[58:61]
	v_mfma_f32_16x16x32_bf16 v[46:49], v[152:155], v[204:207], v[46:49]
	v_mfma_f32_16x16x32_bf16 v[42:45], v[168:171], v[204:207], v[42:45]
	v_mfma_f32_16x16x32_bf16 v[30:33], v[152:155], v[212:215], v[30:33]
	v_mfma_f32_16x16x32_bf16 v[26:29], v[168:171], v[212:215], v[26:29]
	v_mfma_f32_16x16x32_bf16 v[14:17], v[152:155], v[220:223], v[14:17]
	v_mfma_f32_16x16x32_bf16 v[10:13], v[168:171], v[220:223], v[10:13]
	s_setprio 0
	s_setprio 1
	v_mfma_f32_16x16x32_bf16 v[54:57], v[172:175], v[188:191], v[54:57]
	v_mfma_f32_16x16x32_bf16 v[50:53], v[180:183], v[188:191], v[50:53]
	v_mfma_f32_16x16x32_bf16 v[38:41], v[172:175], v[200:203], v[38:41]
	v_mfma_f32_16x16x32_bf16 v[34:37], v[180:183], v[200:203], v[34:37]
	v_mfma_f32_16x16x32_bf16 v[22:25], v[172:175], v[208:211], v[22:25]
	v_mfma_f32_16x16x32_bf16 v[18:21], v[180:183], v[208:211], v[18:21]
	v_mfma_f32_16x16x32_bf16 v[6:9], v[172:175], v[216:219], v[6:9]
	v_mfma_f32_16x16x32_bf16 v[2:5], v[180:183], v[216:219], v[2:5]
	v_mfma_f32_16x16x32_bf16 v[54:57], v[176:179], v[192:195], v[54:57]
	v_mfma_f32_16x16x32_bf16 v[50:53], v[184:187], v[192:195], v[50:53]
	v_mfma_f32_16x16x32_bf16 v[38:41], v[176:179], v[204:207], v[38:41]
	v_mfma_f32_16x16x32_bf16 v[34:37], v[184:187], v[204:207], v[34:37]
	v_mfma_f32_16x16x32_bf16 v[22:25], v[176:179], v[212:215], v[22:25]
	v_mfma_f32_16x16x32_bf16 v[18:21], v[184:187], v[212:215], v[18:21]
	v_mfma_f32_16x16x32_bf16 v[6:9], v[176:179], v[220:223], v[6:9]
	v_mfma_f32_16x16x32_bf16 v[2:5], v[184:187], v[220:223], v[2:5]
	s_setprio 0
	s_add_i32 s85, s85, 2
	s_add_u32 s52, s52, 0x100
	s_addc_u32 s53, s53, 0
	s_add_u32 s83, s83, 0x100
	s_addc_u32 s84, s84, 0
	s_cmp_gt_u32 s85, 13
	s_barrier
	s_cbranch_scc0 .LBB0_289
	s_and_b64 vcc, exec, s[18:19]
	s_cbranch_vccz .LBB0_292
	s_barrier

.LBB0_557:
	ds_read_b128 v[130:133], v190
	ds_read_b128 v[134:137], v190 offset:1024
	ds_read_b128 v[138:141], v190 offset:2048
	ds_read_b128 v[142:145], v190 offset:3072
	ds_read_b128 v[146:149], v191
	ds_read_b128 v[150:153], v191 offset:1024
	ds_read_b128 v[170:173], v191 offset:2048
	ds_read_b128 v[174:177], v191 offset:3072
	s_add_u32 s54, s52, 0xfffc0080
	s_addc_u32 s55, s53, -1
	s_cmp_eq_u32 s78, 12
	s_cselect_b32 s57, s47, s55
	s_cselect_b32 s56, s74, s54
	s_cselect_b32 s55, s29, s77
	s_cselect_b32 s54, s75, s76
	v_lshl_add_u64 v[186:187], s[52:53], 0, v[162:163]
	s_add_i32 m0, s11, 0xc000
	ds_read_b128 v[178:181], v192
	ds_read_b128 v[182:185], v192 offset:1024
	ds_read_b128 v[194:197], v192 offset:2048
	ds_read_b128 v[200:203], v192 offset:3072
	ds_read_b128 v[204:207], v192 offset:4096
	ds_read_b128 v[208:211], v192 offset:5120
	ds_read_b128 v[212:215], v192 offset:6144
	ds_read_b128 v[216:219], v192 offset:7168
	global_load_lds_dwordx4 v[186:187], off
	v_lshl_add_u64 v[186:187], s[52:53], 0, v[164:165]
	s_add_i32 m0, s11, 0xe000
	s_nop 0
	global_load_lds_dwordx4 v[186:187], off
	s_waitcnt vmcnt(8)
	s_waitcnt lgkmcnt(0)
	s_barrier
	s_setprio 1
	s_waitcnt lgkmcnt(0)
	v_mfma_f32_16x16x32_bf16 v[126:129], v[130:133], v[178:181], v[126:129]
	v_mfma_f32_16x16x32_bf16 v[122:125], v[138:141], v[178:181], v[122:125]
	v_mfma_f32_16x16x32_bf16 v[110:113], v[130:133], v[194:197], v[110:113]
	v_mfma_f32_16x16x32_bf16 v[106:109], v[138:141], v[194:197], v[106:109]
	v_mfma_f32_16x16x32_bf16 v[94:97], v[130:133], v[204:207], v[94:97]
	v_mfma_f32_16x16x32_bf16 v[90:93], v[138:141], v[204:207], v[90:93]
	v_mfma_f32_16x16x32_bf16 v[78:81], v[130:133], v[212:215], v[78:81]
	v_mfma_f32_16x16x32_bf16 v[74:77], v[138:141], v[212:215], v[74:77]
	v_mfma_f32_16x16x32_bf16 v[126:129], v[134:137], v[182:185], v[126:129]
	v_mfma_f32_16x16x32_bf16 v[122:125], v[142:145], v[182:185], v[122:125]
	v_mfma_f32_16x16x32_bf16 v[110:113], v[134:137], v[200:203], v[110:113]
	v_mfma_f32_16x16x32_bf16 v[106:109], v[142:145], v[200:203], v[106:109]
	v_mfma_f32_16x16x32_bf16 v[94:97], v[134:137], v[208:211], v[94:97]
	v_mfma_f32_16x16x32_bf16 v[90:93], v[142:145], v[208:211], v[90:93]
	v_mfma_f32_16x16x32_bf16 v[78:81], v[134:137], v[216:219], v[78:81]
	v_mfma_f32_16x16x32_bf16 v[74:77], v[142:145], v[216:219], v[74:77]
	s_setprio 0
	s_setprio 1
	v_mfma_f32_16x16x32_bf16 v[118:121], v[146:149], v[178:181], v[118:121]
	v_mfma_f32_16x16x32_bf16 v[114:117], v[170:173], v[178:181], v[114:117]
	v_mfma_f32_16x16x32_bf16 v[102:105], v[146:149], v[194:197], v[102:105]
	v_mfma_f32_16x16x32_bf16 v[98:101], v[170:173], v[194:197], v[98:101]
	v_mfma_f32_16x16x32_bf16 v[86:89], v[146:149], v[204:207], v[86:89]
	v_mfma_f32_16x16x32_bf16 v[82:85], v[170:173], v[204:207], v[82:85]
	v_mfma_f32_16x16x32_bf16 v[70:73], v[146:149], v[212:215], v[70:73]
	v_mfma_f32_16x16x32_bf16 v[66:69], v[170:173], v[212:215], v[66:69]
	v_mfma_f32_16x16x32_bf16 v[118:121], v[150:153], v[182:185], v[118:121]
	v_mfma_f32_16x16x32_bf16 v[114:117], v[174:177], v[182:185], v[114:117]
	v_mfma_f32_16x16x32_bf16 v[102:105], v[150:153], v[200:203], v[102:105]
	v_mfma_f32_16x16x32_bf16 v[98:101], v[174:177], v[200:203], v[98:101]
	v_mfma_f32_16x16x32_bf16 v[86:89], v[150:153], v[208:211], v[86:89]
	v_mfma_f32_16x16x32_bf16 v[82:85], v[174:177], v[208:211], v[82:85]
	v_mfma_f32_16x16x32_bf16 v[70:73], v[150:153], v[216:219], v[70:73]
	v_mfma_f32_16x16x32_bf16 v[66:69], v[174:177], v[216:219], v[66:69]
	s_setprio 0
	s_barrier
	ds_read_b128 v[178:181], v192 offset:16384
	ds_read_b128 v[182:185], v192 offset:17408
	ds_read_b128 v[194:197], v192 offset:18432
	ds_read_b128 v[200:203], v192 offset:19456
	ds_read_b128 v[204:207], v192 offset:20480
	ds_read_b128 v[208:211], v192 offset:21504
	ds_read_b128 v[212:215], v192 offset:22528
	ds_read_b128 v[216:219], v192 offset:23552
	s_add_i32 s79, s71, s62
	s_mov_b32 m0, s79
	v_lshl_add_u64 v[186:187], s[54:55], 0, v[156:157]
	global_load_lds_dwordx4 v[186:187], off
	s_add_i32 m0, s79, 0x2000
	s_add_u32 s80, s54, 0x40000
	v_lshl_add_u64 v[220:221], s[54:55], 0, v[160:161]
	s_addc_u32 s81, s55, 0
	s_add_i32 s79, s72, s62
	global_load_lds_dwordx4 v[220:221], off
	v_lshl_add_u64 v[222:223], s[80:81], 0, v[156:157]
	s_mov_b32 m0, s79
	v_lshl_add_u64 v[224:225], s[56:57], 0, v[158:159]
	global_load_lds_dwordx4 v[222:223], off
	v_lshl_add_u64 v[222:223], s[80:81], 0, v[160:161]
	s_add_i32 m0, s79, 0x2000
	s_nop 0
	global_load_lds_dwordx4 v[222:223], off
	v_lshl_add_u64 v[222:223], s[56:57], 0, v[154:155]
	s_mov_b32 m0, s11
	s_nop 0
	global_load_lds_dwordx4 v[222:223], off
	s_mov_b32 m0, s63
	s_nop 0
	global_load_lds_dwordx4 v[224:225], off
	s_waitcnt vmcnt(8)
	s_waitcnt lgkmcnt(0)
	s_barrier
	s_setprio 1
	s_waitcnt lgkmcnt(0)
	v_mfma_f32_16x16x32_bf16 v[62:65], v[130:133], v[178:181], v[62:65]
	v_mfma_f32_16x16x32_bf16 v[58:61], v[138:141], v[178:181], v[58:61]
	v_mfma_f32_16x16x32_bf16 v[46:49], v[130:133], v[194:197], v[46:49]
	v_mfma_f32_16x16x32_bf16 v[42:45], v[138:141], v[194:197], v[42:45]
	v_mfma_f32_16x16x32_bf16 v[30:33], v[130:133], v[204:207], v[30:33]
	v_mfma_f32_16x16x32_bf16 v[26:29], v[138:141], v[204:207], v[26:29]
	v_mfma_f32_16x16x32_bf16 v[14:17], v[130:133], v[212:215], v[14:17]
	v_mfma_f32_16x16x32_bf16 v[10:13], v[138:141], v[212:215], v[10:13]
	v_mfma_f32_16x16x32_bf16 v[62:65], v[134:137], v[182:185], v[62:65]
	v_mfma_f32_16x16x32_bf16 v[58:61], v[142:145], v[182:185], v[58:61]
	v_mfma_f32_16x16x32_bf16 v[46:49], v[134:137], v[200:203], v[46:49]
	v_mfma_f32_16x16x32_bf16 v[42:45], v[142:145], v[200:203], v[42:45]
	v_mfma_f32_16x16x32_bf16 v[30:33], v[134:137], v[208:211], v[30:33]
	v_mfma_f32_16x16x32_bf16 v[26:29], v[142:145], v[208:211], v[26:29]
	v_mfma_f32_16x16x32_bf16 v[14:17], v[134:137], v[216:219], v[14:17]
	v_mfma_f32_16x16x32_bf16 v[10:13], v[142:145], v[216:219], v[10:13]
	s_setprio 0
	s_setprio 1
	v_mfma_f32_16x16x32_bf16 v[54:57], v[146:149], v[178:181], v[54:57]
	v_mfma_f32_16x16x32_bf16 v[50:53], v[170:173], v[178:181], v[50:53]
	v_mfma_f32_16x16x32_bf16 v[38:41], v[146:149], v[194:197], v[38:41]
	v_mfma_f32_16x16x32_bf16 v[34:37], v[170:173], v[194:197], v[34:37]
	v_mfma_f32_16x16x32_bf16 v[22:25], v[146:149], v[204:207], v[22:25]
	v_mfma_f32_16x16x32_bf16 v[18:21], v[170:173], v[204:207], v[18:21]
	v_mfma_f32_16x16x32_bf16 v[6:9], v[146:149], v[212:215], v[6:9]
	v_mfma_f32_16x16x32_bf16 v[2:5], v[170:173], v[212:215], v[2:5]
	v_mfma_f32_16x16x32_bf16 v[54:57], v[150:153], v[182:185], v[54:57]
	v_mfma_f32_16x16x32_bf16 v[50:53], v[174:177], v[182:185], v[50:53]
	v_mfma_f32_16x16x32_bf16 v[38:41], v[150:153], v[200:203], v[38:41]
	v_mfma_f32_16x16x32_bf16 v[34:37], v[174:177], v[200:203], v[34:37]
	v_mfma_f32_16x16x32_bf16 v[22:25], v[150:153], v[208:211], v[22:25]
	v_mfma_f32_16x16x32_bf16 v[18:21], v[174:177], v[208:211], v[18:21]
	v_mfma_f32_16x16x32_bf16 v[6:9], v[150:153], v[216:219], v[6:9]
	v_mfma_f32_16x16x32_bf16 v[2:5], v[174:177], v[216:219], v[2:5]
	s_setprio 0
	s_barrier
	s_add_i32 s79, 0, 0x18000
	s_add_i32 s80, 0, 0x1c000
	v_add_u32_e32 v142, s79, v188
	v_add_u32_e32 v174, s80, v188
	ds_read_b128 v[130:133], v142
	ds_read_b128 v[134:137], v142 offset:1024
	ds_read_b128 v[138:141], v142 offset:2048
	ds_read_b128 v[142:145], v142 offset:3072
	ds_read_b128 v[146:149], v174
	ds_read_b128 v[150:153], v174 offset:1024
	ds_read_b128 v[170:173], v174 offset:2048
	ds_read_b128 v[174:177], v174 offset:3072
	s_add_u32 s56, s56, 0x40000
	s_addc_u32 s57, s57, 0
	s_mov_b32 m0, s64
	v_lshl_add_u64 v[226:227], s[56:57], 0, v[154:155]
	ds_read_b128 v[178:181], v192 offset:32768
	ds_read_b128 v[182:185], v192 offset:33792
	ds_read_b128 v[194:197], v192 offset:34816
	ds_read_b128 v[200:203], v192 offset:35840
	ds_read_b128 v[204:207], v192 offset:36864
	ds_read_b128 v[208:211], v192 offset:37888
	ds_read_b128 v[212:215], v192 offset:38912
	ds_read_b128 v[216:219], v192 offset:39936
	global_load_lds_dwordx4 v[226:227], off
	v_lshl_add_u64 v[226:227], s[56:57], 0, v[158:159]
	s_mov_b32 m0, s65
	s_nop 0
	global_load_lds_dwordx4 v[226:227], off
	s_waitcnt vmcnt(8)
	s_waitcnt lgkmcnt(0)
	s_barrier
	s_setprio 1
	s_waitcnt lgkmcnt(0)
	v_mfma_f32_16x16x32_bf16 v[126:129], v[130:133], v[178:181], v[126:129]
	v_mfma_f32_16x16x32_bf16 v[122:125], v[138:141], v[178:181], v[122:125]
	v_mfma_f32_16x16x32_bf16 v[110:113], v[130:133], v[194:197], v[110:113]
	v_mfma_f32_16x16x32_bf16 v[106:109], v[138:141], v[194:197], v[106:109]
	v_mfma_f32_16x16x32_bf16 v[94:97], v[130:133], v[204:207], v[94:97]
	v_mfma_f32_16x16x32_bf16 v[90:93], v[138:141], v[204:207], v[90:93]
	v_mfma_f32_16x16x32_bf16 v[78:81], v[130:133], v[212:215], v[78:81]
	v_mfma_f32_16x16x32_bf16 v[74:77], v[138:141], v[212:215], v[74:77]
	v_mfma_f32_16x16x32_bf16 v[126:129], v[134:137], v[182:185], v[126:129]
	v_mfma_f32_16x16x32_bf16 v[122:125], v[142:145], v[182:185], v[122:125]
	v_mfma_f32_16x16x32_bf16 v[110:113], v[134:137], v[200:203], v[110:113]
	v_mfma_f32_16x16x32_bf16 v[106:109], v[142:145], v[200:203], v[106:109]
	v_mfma_f32_16x16x32_bf16 v[94:97], v[134:137], v[208:211], v[94:97]
	v_mfma_f32_16x16x32_bf16 v[90:93], v[142:145], v[208:211], v[90:93]
	v_mfma_f32_16x16x32_bf16 v[78:81], v[134:137], v[216:219], v[78:81]
	v_mfma_f32_16x16x32_bf16 v[74:77], v[142:145], v[216:219], v[74:77]
	s_setprio 0
	s_setprio 1
	v_mfma_f32_16x16x32_bf16 v[118:121], v[146:149], v[178:181], v[118:121]
	v_mfma_f32_16x16x32_bf16 v[114:117], v[170:173], v[178:181], v[114:117]
	v_mfma_f32_16x16x32_bf16 v[102:105], v[146:149], v[194:197], v[102:105]
	v_mfma_f32_16x16x32_bf16 v[98:101], v[170:173], v[194:197], v[98:101]
	v_mfma_f32_16x16x32_bf16 v[86:89], v[146:149], v[204:207], v[86:89]
	v_mfma_f32_16x16x32_bf16 v[82:85], v[170:173], v[204:207], v[82:85]
	v_mfma_f32_16x16x32_bf16 v[70:73], v[146:149], v[212:215], v[70:73]
	v_mfma_f32_16x16x32_bf16 v[66:69], v[170:173], v[212:215], v[66:69]
	v_mfma_f32_16x16x32_bf16 v[118:121], v[150:153], v[182:185], v[118:121]
	v_mfma_f32_16x16x32_bf16 v[114:117], v[174:177], v[182:185], v[114:117]
	v_mfma_f32_16x16x32_bf16 v[102:105], v[150:153], v[200:203], v[102:105]
	v_mfma_f32_16x16x32_bf16 v[98:101], v[174:177], v[200:203], v[98:101]
	v_mfma_f32_16x16x32_bf16 v[86:89], v[150:153], v[208:211], v[86:89]
	v_mfma_f32_16x16x32_bf16 v[82:85], v[174:177], v[208:211], v[82:85]
	v_mfma_f32_16x16x32_bf16 v[70:73], v[150:153], v[216:219], v[70:73]
	v_mfma_f32_16x16x32_bf16 v[66:69], v[174:177], v[216:219], v[66:69]
	s_setprio 0
	s_barrier
	ds_read_b128 v[178:181], v192 offset:49152
	ds_read_b128 v[182:185], v192 offset:50176
	ds_read_b128 v[194:197], v192 offset:51200
	ds_read_b128 v[200:203], v192 offset:52224
	ds_read_b128 v[204:207], v192 offset:53248
	ds_read_b128 v[208:211], v192 offset:54272
	ds_read_b128 v[212:215], v192 offset:55296
	ds_read_b128 v[216:219], v192 offset:56320
	s_add_i32 s56, s79, s62
	s_mov_b32 m0, s56
	v_lshl_add_u64 v[186:187], v[186:187], 0, s[18:19]
	global_load_lds_dwordx4 v[186:187], off
	s_add_i32 m0, s56, 0x2000
	s_add_u32 s54, s54, 0x40080
	v_lshl_add_u64 v[186:187], v[220:221], 0, s[18:19]
	s_addc_u32 s55, s55, 0
	s_add_i32 s56, s80, s62
	global_load_lds_dwordx4 v[186:187], off
	v_lshl_add_u64 v[186:187], s[54:55], 0, v[156:157]
	s_mov_b32 m0, s56
	s_nop 0
	global_load_lds_dwordx4 v[186:187], off
	v_lshl_add_u64 v[186:187], s[54:55], 0, v[160:161]
	s_add_i32 m0, s56, 0x2000
	s_nop 0
	global_load_lds_dwordx4 v[186:187], off
	v_lshl_add_u64 v[186:187], v[222:223], 0, s[18:19]
	s_mov_b32 m0, s67
	s_nop 0
	global_load_lds_dwordx4 v[186:187], off
	v_lshl_add_u64 v[186:187], v[224:225], 0, s[18:19]
	s_mov_b32 m0, s68
	s_nop 0
	global_load_lds_dwordx4 v[186:187], off
	s_waitcnt vmcnt(8)
	s_waitcnt lgkmcnt(0)
	s_barrier
	s_setprio 1
	s_waitcnt lgkmcnt(0)
	v_mfma_f32_16x16x32_bf16 v[62:65], v[130:133], v[178:181], v[62:65]
	v_mfma_f32_16x16x32_bf16 v[58:61], v[138:141], v[178:181], v[58:61]
	v_mfma_f32_16x16x32_bf16 v[46:49], v[130:133], v[194:197], v[46:49]
	v_mfma_f32_16x16x32_bf16 v[42:45], v[138:141], v[194:197], v[42:45]
	v_mfma_f32_16x16x32_bf16 v[30:33], v[130:133], v[204:207], v[30:33]
	v_mfma_f32_16x16x32_bf16 v[26:29], v[138:141], v[204:207], v[26:29]
	v_mfma_f32_16x16x32_bf16 v[14:17], v[130:133], v[212:215], v[14:17]
	v_mfma_f32_16x16x32_bf16 v[10:13], v[138:141], v[212:215], v[10:13]
	v_mfma_f32_16x16x32_bf16 v[62:65], v[134:137], v[182:185], v[62:65]
	v_mfma_f32_16x16x32_bf16 v[58:61], v[142:145], v[182:185], v[58:61]
	v_mfma_f32_16x16x32_bf16 v[46:49], v[134:137], v[200:203], v[46:49]
	v_mfma_f32_16x16x32_bf16 v[42:45], v[142:145], v[200:203], v[42:45]
	v_mfma_f32_16x16x32_bf16 v[30:33], v[134:137], v[208:211], v[30:33]
	v_mfma_f32_16x16x32_bf16 v[26:29], v[142:145], v[208:211], v[26:29]
	v_mfma_f32_16x16x32_bf16 v[14:17], v[134:137], v[216:219], v[14:17]
	v_mfma_f32_16x16x32_bf16 v[10:13], v[142:145], v[216:219], v[10:13]
	s_setprio 0
	s_setprio 1
	v_mfma_f32_16x16x32_bf16 v[54:57], v[146:149], v[178:181], v[54:57]
	v_mfma_f32_16x16x32_bf16 v[50:53], v[170:173], v[178:181], v[50:53]
	v_mfma_f32_16x16x32_bf16 v[38:41], v[146:149], v[194:197], v[38:41]
	v_mfma_f32_16x16x32_bf16 v[34:37], v[170:173], v[194:197], v[34:37]
	v_mfma_f32_16x16x32_bf16 v[22:25], v[146:149], v[204:207], v[22:25]
	v_mfma_f32_16x16x32_bf16 v[18:21], v[170:173], v[204:207], v[18:21]
	v_mfma_f32_16x16x32_bf16 v[6:9], v[146:149], v[212:215], v[6:9]
	v_mfma_f32_16x16x32_bf16 v[2:5], v[170:173], v[212:215], v[2:5]
	v_mfma_f32_16x16x32_bf16 v[54:57], v[150:153], v[182:185], v[54:57]
	v_mfma_f32_16x16x32_bf16 v[50:53], v[174:177], v[182:185], v[50:53]
	v_mfma_f32_16x16x32_bf16 v[38:41], v[150:153], v[200:203], v[38:41]
	v_mfma_f32_16x16x32_bf16 v[34:37], v[174:177], v[200:203], v[34:37]
	v_mfma_f32_16x16x32_bf16 v[22:25], v[150:153], v[208:211], v[22:25]
	v_mfma_f32_16x16x32_bf16 v[18:21], v[174:177], v[208:211], v[18:21]
	v_mfma_f32_16x16x32_bf16 v[6:9], v[150:153], v[216:219], v[6:9]
	v_mfma_f32_16x16x32_bf16 v[2:5], v[174:177], v[216:219], v[2:5]
	s_setprio 0
	s_add_i32 s78, s78, 2
	s_add_u32 s52, s52, 0x100
	s_addc_u32 s53, s53, 0
	s_add_u32 s76, s76, 0x100
	s_addc_u32 s77, s77, 0
	s_cmp_gt_u32 s78, 13
	s_barrier
	s_cbranch_scc0 .LBB0_557
	s_and_b64 vcc, exec, s[20:21]
	s_cbranch_vccz .LBB0_560
	s_barrier

.LBB0_713:
	ds_read_b128 v[130:133], v243
	ds_read_b128 v[134:137], v243 offset:1024
	ds_read_b128 v[138:141], v243 offset:2048
	ds_read_b128 v[142:145], v243 offset:3072
	ds_read_b128 v[146:149], v244
	ds_read_b128 v[150:153], v244 offset:1024
	ds_read_b128 v[154:157], v244 offset:2048
	ds_read_b128 v[158:161], v244 offset:3072
	s_add_u32 s62, s12, 0xfffc0080
	s_addc_u32 s63, s13, -1
	s_cmp_eq_u32 s95, 12
	s_cselect_b32 s65, s57, s63
	s_cselect_b32 s64, s67, s62
	s_cselect_b32 s63, s55, s94
	s_cselect_b32 s62, s92, s93
	v_lshl_add_u64 v[194:195], s[12:13], 0, v[216:217]
	s_add_i32 m0, s25, 0xc000
	ds_read_b128 v[162:165], v245
	ds_read_b128 v[166:169], v245 offset:1024
	ds_read_b128 v[170:173], v245 offset:2048
	ds_read_b128 v[174:177], v245 offset:3072
	ds_read_b128 v[178:181], v245 offset:4096
	ds_read_b128 v[182:185], v245 offset:5120
	ds_read_b128 v[186:189], v245 offset:6144
	ds_read_b128 v[190:193], v245 offset:7168
	global_load_lds_dwordx4 v[194:195], off
	v_lshl_add_u64 v[194:195], s[12:13], 0, v[218:219]
	s_add_i32 m0, s25, 0xe000
	s_nop 0
	global_load_lds_dwordx4 v[194:195], off
	s_waitcnt vmcnt(8)
	s_waitcnt lgkmcnt(0)
	s_barrier
	s_setprio 1
	s_waitcnt lgkmcnt(0)
	v_mfma_f32_16x16x32_bf16 v[126:129], v[130:133], v[162:165], v[126:129]
	v_mfma_f32_16x16x32_bf16 v[122:125], v[138:141], v[162:165], v[122:125]
	v_mfma_f32_16x16x32_bf16 v[110:113], v[130:133], v[170:173], v[110:113]
	v_mfma_f32_16x16x32_bf16 v[106:109], v[138:141], v[170:173], v[106:109]
	v_mfma_f32_16x16x32_bf16 v[94:97], v[130:133], v[178:181], v[94:97]
	v_mfma_f32_16x16x32_bf16 v[90:93], v[138:141], v[178:181], v[90:93]
	v_mfma_f32_16x16x32_bf16 v[78:81], v[130:133], v[186:189], v[78:81]
	v_mfma_f32_16x16x32_bf16 v[74:77], v[138:141], v[186:189], v[74:77]
	v_mfma_f32_16x16x32_bf16 v[126:129], v[134:137], v[166:169], v[126:129]
	v_mfma_f32_16x16x32_bf16 v[122:125], v[142:145], v[166:169], v[122:125]
	v_mfma_f32_16x16x32_bf16 v[110:113], v[134:137], v[174:177], v[110:113]
	v_mfma_f32_16x16x32_bf16 v[106:109], v[142:145], v[174:177], v[106:109]
	v_mfma_f32_16x16x32_bf16 v[94:97], v[134:137], v[182:185], v[94:97]
	v_mfma_f32_16x16x32_bf16 v[90:93], v[142:145], v[182:185], v[90:93]
	v_mfma_f32_16x16x32_bf16 v[78:81], v[134:137], v[190:193], v[78:81]
	v_mfma_f32_16x16x32_bf16 v[74:77], v[142:145], v[190:193], v[74:77]
	s_setprio 0
	s_setprio 1
	v_mfma_f32_16x16x32_bf16 v[118:121], v[146:149], v[162:165], v[118:121]
	v_mfma_f32_16x16x32_bf16 v[114:117], v[154:157], v[162:165], v[114:117]
	v_mfma_f32_16x16x32_bf16 v[102:105], v[146:149], v[170:173], v[102:105]
	v_mfma_f32_16x16x32_bf16 v[98:101], v[154:157], v[170:173], v[98:101]
	v_mfma_f32_16x16x32_bf16 v[86:89], v[146:149], v[178:181], v[86:89]
	v_mfma_f32_16x16x32_bf16 v[82:85], v[154:157], v[178:181], v[82:85]
	v_mfma_f32_16x16x32_bf16 v[70:73], v[146:149], v[186:189], v[70:73]
	v_mfma_f32_16x16x32_bf16 v[66:69], v[154:157], v[186:189], v[66:69]
	v_mfma_f32_16x16x32_bf16 v[118:121], v[150:153], v[166:169], v[118:121]
	v_mfma_f32_16x16x32_bf16 v[114:117], v[158:161], v[166:169], v[114:117]
	v_mfma_f32_16x16x32_bf16 v[102:105], v[150:153], v[174:177], v[102:105]
	v_mfma_f32_16x16x32_bf16 v[98:101], v[158:161], v[174:177], v[98:101]
	v_mfma_f32_16x16x32_bf16 v[86:89], v[150:153], v[182:185], v[86:89]
	v_mfma_f32_16x16x32_bf16 v[82:85], v[158:161], v[182:185], v[82:85]
	v_mfma_f32_16x16x32_bf16 v[70:73], v[150:153], v[190:193], v[70:73]
	v_mfma_f32_16x16x32_bf16 v[66:69], v[158:161], v[190:193], v[66:69]
	s_setprio 0
	s_barrier
	ds_read_b128 v[162:165], v245 offset:16384
	ds_read_b128 v[166:169], v245 offset:17408
	ds_read_b128 v[170:173], v245 offset:18432
	ds_read_b128 v[174:177], v245 offset:19456
	ds_read_b128 v[178:181], v245 offset:20480
	ds_read_b128 v[182:185], v245 offset:21504
	ds_read_b128 v[186:189], v245 offset:22528
	ds_read_b128 v[190:193], v245 offset:23552
	s_add_i32 s96, s85, s73
	s_mov_b32 m0, s96
	v_lshl_add_u64 v[194:195], s[62:63], 0, v[202:203]
	global_load_lds_dwordx4 v[194:195], off
	s_add_i32 m0, s96, 0x2000
	s_add_u32 s96, s62, 0x40000
	v_lshl_add_u64 v[196:197], s[62:63], 0, v[206:207]
	s_addc_u32 s97, s63, 0
	s_add_i32 vcc_lo, s86, s73
	global_load_lds_dwordx4 v[196:197], off
	v_lshl_add_u64 v[220:221], s[96:97], 0, v[202:203]
	s_mov_b32 m0, vcc_lo
	v_lshl_add_u64 v[222:223], s[64:65], 0, v[204:205]
	global_load_lds_dwordx4 v[220:221], off
	v_lshl_add_u64 v[220:221], s[96:97], 0, v[206:207]
	s_add_i32 m0, vcc_lo, 0x2000
	s_nop 0
	global_load_lds_dwordx4 v[220:221], off
	v_lshl_add_u64 v[220:221], s[64:65], 0, v[200:201]
	s_mov_b32 m0, s25
	s_nop 0
	global_load_lds_dwordx4 v[220:221], off
	s_mov_b32 m0, s74
	s_nop 0
	global_load_lds_dwordx4 v[222:223], off
	s_waitcnt vmcnt(8)
	s_waitcnt lgkmcnt(0)
	s_barrier
	s_setprio 1
	s_waitcnt lgkmcnt(0)
	v_mfma_f32_16x16x32_bf16 v[62:65], v[130:133], v[162:165], v[62:65]
	v_mfma_f32_16x16x32_bf16 v[58:61], v[138:141], v[162:165], v[58:61]
	v_mfma_f32_16x16x32_bf16 v[46:49], v[130:133], v[170:173], v[46:49]
	v_mfma_f32_16x16x32_bf16 v[42:45], v[138:141], v[170:173], v[42:45]
	v_mfma_f32_16x16x32_bf16 v[30:33], v[130:133], v[178:181], v[30:33]
	v_mfma_f32_16x16x32_bf16 v[26:29], v[138:141], v[178:181], v[26:29]
	v_mfma_f32_16x16x32_bf16 v[14:17], v[130:133], v[186:189], v[14:17]
	v_mfma_f32_16x16x32_bf16 v[10:13], v[138:141], v[186:189], v[10:13]
	v_mfma_f32_16x16x32_bf16 v[62:65], v[134:137], v[166:169], v[62:65]
	v_mfma_f32_16x16x32_bf16 v[58:61], v[142:145], v[166:169], v[58:61]
	v_mfma_f32_16x16x32_bf16 v[46:49], v[134:137], v[174:177], v[46:49]
	v_mfma_f32_16x16x32_bf16 v[42:45], v[142:145], v[174:177], v[42:45]
	v_mfma_f32_16x16x32_bf16 v[30:33], v[134:137], v[182:185], v[30:33]
	v_mfma_f32_16x16x32_bf16 v[26:29], v[142:145], v[182:185], v[26:29]
	v_mfma_f32_16x16x32_bf16 v[14:17], v[134:137], v[190:193], v[14:17]
	v_mfma_f32_16x16x32_bf16 v[10:13], v[142:145], v[190:193], v[10:13]
	s_setprio 0
	s_setprio 1
	v_mfma_f32_16x16x32_bf16 v[54:57], v[146:149], v[162:165], v[54:57]
	v_mfma_f32_16x16x32_bf16 v[50:53], v[154:157], v[162:165], v[50:53]
	v_mfma_f32_16x16x32_bf16 v[38:41], v[146:149], v[170:173], v[38:41]
	v_mfma_f32_16x16x32_bf16 v[34:37], v[154:157], v[170:173], v[34:37]
	v_mfma_f32_16x16x32_bf16 v[22:25], v[146:149], v[178:181], v[22:25]
	v_mfma_f32_16x16x32_bf16 v[18:21], v[154:157], v[178:181], v[18:21]
	v_mfma_f32_16x16x32_bf16 v[6:9], v[146:149], v[186:189], v[6:9]
	v_mfma_f32_16x16x32_bf16 v[2:5], v[154:157], v[186:189], v[2:5]
	v_mfma_f32_16x16x32_bf16 v[54:57], v[150:153], v[166:169], v[54:57]
	v_mfma_f32_16x16x32_bf16 v[50:53], v[158:161], v[166:169], v[50:53]
	v_mfma_f32_16x16x32_bf16 v[38:41], v[150:153], v[174:177], v[38:41]
	v_mfma_f32_16x16x32_bf16 v[34:37], v[158:161], v[174:177], v[34:37]
	v_mfma_f32_16x16x32_bf16 v[22:25], v[150:153], v[182:185], v[22:25]
	v_mfma_f32_16x16x32_bf16 v[18:21], v[158:161], v[182:185], v[18:21]
	v_mfma_f32_16x16x32_bf16 v[6:9], v[150:153], v[190:193], v[6:9]
	v_mfma_f32_16x16x32_bf16 v[2:5], v[158:161], v[190:193], v[2:5]
	s_setprio 0
	s_barrier
	s_add_i32 s96, 0, 0x18000
	s_add_i32 s97, 0, 0x1c000
	v_add_u32_e32 v142, s96, v199
	v_add_u32_e32 v158, s97, v199
	ds_read_b128 v[130:133], v142
	ds_read_b128 v[134:137], v142 offset:1024
	ds_read_b128 v[138:141], v142 offset:2048
	ds_read_b128 v[142:145], v142 offset:3072
	ds_read_b128 v[146:149], v158
	ds_read_b128 v[150:153], v158 offset:1024
	ds_read_b128 v[154:157], v158 offset:2048
	ds_read_b128 v[158:161], v158 offset:3072
	s_add_u32 s64, s64, 0x40000
	s_addc_u32 s65, s65, 0
	s_mov_b32 m0, s75
	v_lshl_add_u64 v[224:225], s[64:65], 0, v[200:201]
	ds_read_b128 v[162:165], v245 offset:32768
	ds_read_b128 v[166:169], v245 offset:33792
	ds_read_b128 v[170:173], v245 offset:34816
	ds_read_b128 v[174:177], v245 offset:35840
	ds_read_b128 v[178:181], v245 offset:36864
	ds_read_b128 v[182:185], v245 offset:37888
	ds_read_b128 v[186:189], v245 offset:38912
	ds_read_b128 v[190:193], v245 offset:39936
	global_load_lds_dwordx4 v[224:225], off
	v_lshl_add_u64 v[224:225], s[64:65], 0, v[204:205]
	s_mov_b32 m0, s76
	s_nop 0
	global_load_lds_dwordx4 v[224:225], off
	s_waitcnt vmcnt(8)
	s_waitcnt lgkmcnt(0)
	s_barrier
	s_setprio 1
	s_waitcnt lgkmcnt(0)
	v_mfma_f32_16x16x32_bf16 v[126:129], v[130:133], v[162:165], v[126:129]
	v_mfma_f32_16x16x32_bf16 v[122:125], v[138:141], v[162:165], v[122:125]
	v_mfma_f32_16x16x32_bf16 v[110:113], v[130:133], v[170:173], v[110:113]
	v_mfma_f32_16x16x32_bf16 v[106:109], v[138:141], v[170:173], v[106:109]
	v_mfma_f32_16x16x32_bf16 v[94:97], v[130:133], v[178:181], v[94:97]
	v_mfma_f32_16x16x32_bf16 v[90:93], v[138:141], v[178:181], v[90:93]
	v_mfma_f32_16x16x32_bf16 v[78:81], v[130:133], v[186:189], v[78:81]
	v_mfma_f32_16x16x32_bf16 v[74:77], v[138:141], v[186:189], v[74:77]
	v_mfma_f32_16x16x32_bf16 v[126:129], v[134:137], v[166:169], v[126:129]
	v_mfma_f32_16x16x32_bf16 v[122:125], v[142:145], v[166:169], v[122:125]
	v_mfma_f32_16x16x32_bf16 v[110:113], v[134:137], v[174:177], v[110:113]
	v_mfma_f32_16x16x32_bf16 v[106:109], v[142:145], v[174:177], v[106:109]
	v_mfma_f32_16x16x32_bf16 v[94:97], v[134:137], v[182:185], v[94:97]
	v_mfma_f32_16x16x32_bf16 v[90:93], v[142:145], v[182:185], v[90:93]
	v_mfma_f32_16x16x32_bf16 v[78:81], v[134:137], v[190:193], v[78:81]
	v_mfma_f32_16x16x32_bf16 v[74:77], v[142:145], v[190:193], v[74:77]
	s_setprio 0
	s_setprio 1
	v_mfma_f32_16x16x32_bf16 v[118:121], v[146:149], v[162:165], v[118:121]
	v_mfma_f32_16x16x32_bf16 v[114:117], v[154:157], v[162:165], v[114:117]
	v_mfma_f32_16x16x32_bf16 v[102:105], v[146:149], v[170:173], v[102:105]
	v_mfma_f32_16x16x32_bf16 v[98:101], v[154:157], v[170:173], v[98:101]
	v_mfma_f32_16x16x32_bf16 v[86:89], v[146:149], v[178:181], v[86:89]
	v_mfma_f32_16x16x32_bf16 v[82:85], v[154:157], v[178:181], v[82:85]
	v_mfma_f32_16x16x32_bf16 v[70:73], v[146:149], v[186:189], v[70:73]
	v_mfma_f32_16x16x32_bf16 v[66:69], v[154:157], v[186:189], v[66:69]
	v_mfma_f32_16x16x32_bf16 v[118:121], v[150:153], v[166:169], v[118:121]
	v_mfma_f32_16x16x32_bf16 v[114:117], v[158:161], v[166:169], v[114:117]
	v_mfma_f32_16x16x32_bf16 v[102:105], v[150:153], v[174:177], v[102:105]
	v_mfma_f32_16x16x32_bf16 v[98:101], v[158:161], v[174:177], v[98:101]
	v_mfma_f32_16x16x32_bf16 v[86:89], v[150:153], v[182:185], v[86:89]
	v_mfma_f32_16x16x32_bf16 v[82:85], v[158:161], v[182:185], v[82:85]
	v_mfma_f32_16x16x32_bf16 v[70:73], v[150:153], v[190:193], v[70:73]
	v_mfma_f32_16x16x32_bf16 v[66:69], v[158:161], v[190:193], v[66:69]
	s_setprio 0
	s_barrier
	ds_read_b128 v[162:165], v245 offset:49152
	ds_read_b128 v[166:169], v245 offset:50176
	ds_read_b128 v[170:173], v245 offset:51200
	ds_read_b128 v[174:177], v245 offset:52224
	ds_read_b128 v[178:181], v245 offset:53248
	ds_read_b128 v[182:185], v245 offset:54272
	ds_read_b128 v[186:189], v245 offset:55296
	ds_read_b128 v[190:193], v245 offset:56320
	s_add_i32 s64, s96, s73
	s_mov_b32 m0, s64
	v_lshl_add_u64 v[194:195], v[194:195], 0, s[26:27]
	global_load_lds_dwordx4 v[194:195], off
	s_add_i32 m0, s64, 0x2000
	s_add_u32 s62, s62, 0x40080
	v_lshl_add_u64 v[194:195], v[196:197], 0, s[26:27]
	s_addc_u32 s63, s63, 0
	s_add_i32 s64, s97, s73
	global_load_lds_dwordx4 v[194:195], off
	v_lshl_add_u64 v[194:195], s[62:63], 0, v[202:203]
	s_mov_b32 m0, s64
	s_nop 0
	global_load_lds_dwordx4 v[194:195], off
	v_lshl_add_u64 v[194:195], s[62:63], 0, v[206:207]
	s_add_i32 m0, s64, 0x2000
	s_nop 0
	global_load_lds_dwordx4 v[194:195], off
	v_lshl_add_u64 v[194:195], v[220:221], 0, s[26:27]
	s_mov_b32 m0, s77
	s_nop 0
	global_load_lds_dwordx4 v[194:195], off
	v_lshl_add_u64 v[194:195], v[222:223], 0, s[26:27]
	s_mov_b32 m0, s78
	s_nop 0
	global_load_lds_dwordx4 v[194:195], off
	s_waitcnt vmcnt(8)
	s_waitcnt lgkmcnt(0)
	s_barrier
	s_setprio 1
	s_waitcnt lgkmcnt(0)
	v_mfma_f32_16x16x32_bf16 v[62:65], v[130:133], v[162:165], v[62:65]
	v_mfma_f32_16x16x32_bf16 v[58:61], v[138:141], v[162:165], v[58:61]
	v_mfma_f32_16x16x32_bf16 v[46:49], v[130:133], v[170:173], v[46:49]
	v_mfma_f32_16x16x32_bf16 v[42:45], v[138:141], v[170:173], v[42:45]
	v_mfma_f32_16x16x32_bf16 v[30:33], v[130:133], v[178:181], v[30:33]
	v_mfma_f32_16x16x32_bf16 v[26:29], v[138:141], v[178:181], v[26:29]
	v_mfma_f32_16x16x32_bf16 v[14:17], v[130:133], v[186:189], v[14:17]
	v_mfma_f32_16x16x32_bf16 v[10:13], v[138:141], v[186:189], v[10:13]
	v_mfma_f32_16x16x32_bf16 v[62:65], v[134:137], v[166:169], v[62:65]
	v_mfma_f32_16x16x32_bf16 v[58:61], v[142:145], v[166:169], v[58:61]
	v_mfma_f32_16x16x32_bf16 v[46:49], v[134:137], v[174:177], v[46:49]
	v_mfma_f32_16x16x32_bf16 v[42:45], v[142:145], v[174:177], v[42:45]
	v_mfma_f32_16x16x32_bf16 v[30:33], v[134:137], v[182:185], v[30:33]
	v_mfma_f32_16x16x32_bf16 v[26:29], v[142:145], v[182:185], v[26:29]
	v_mfma_f32_16x16x32_bf16 v[14:17], v[134:137], v[190:193], v[14:17]
	v_mfma_f32_16x16x32_bf16 v[10:13], v[142:145], v[190:193], v[10:13]
	s_setprio 0
	s_setprio 1
	v_mfma_f32_16x16x32_bf16 v[54:57], v[146:149], v[162:165], v[54:57]
	v_mfma_f32_16x16x32_bf16 v[50:53], v[154:157], v[162:165], v[50:53]
	v_mfma_f32_16x16x32_bf16 v[38:41], v[146:149], v[170:173], v[38:41]
	v_mfma_f32_16x16x32_bf16 v[34:37], v[154:157], v[170:173], v[34:37]
	v_mfma_f32_16x16x32_bf16 v[22:25], v[146:149], v[178:181], v[22:25]
	v_mfma_f32_16x16x32_bf16 v[18:21], v[154:157], v[178:181], v[18:21]
	v_mfma_f32_16x16x32_bf16 v[6:9], v[146:149], v[186:189], v[6:9]
	v_mfma_f32_16x16x32_bf16 v[2:5], v[154:157], v[186:189], v[2:5]
	v_mfma_f32_16x16x32_bf16 v[54:57], v[150:153], v[166:169], v[54:57]
	v_mfma_f32_16x16x32_bf16 v[50:53], v[158:161], v[166:169], v[50:53]
	v_mfma_f32_16x16x32_bf16 v[38:41], v[150:153], v[174:177], v[38:41]
	v_mfma_f32_16x16x32_bf16 v[34:37], v[158:161], v[174:177], v[34:37]
	v_mfma_f32_16x16x32_bf16 v[22:25], v[150:153], v[182:185], v[22:25]
	v_mfma_f32_16x16x32_bf16 v[18:21], v[158:161], v[182:185], v[18:21]
	v_mfma_f32_16x16x32_bf16 v[6:9], v[150:153], v[190:193], v[6:9]
	v_mfma_f32_16x16x32_bf16 v[2:5], v[158:161], v[190:193], v[2:5]
	s_setprio 0
	s_add_i32 s95, s95, 2
	s_add_u32 s12, s12, 0x100
	s_addc_u32 s13, s13, 0
	s_add_u32 s93, s93, 0x100
	s_addc_u32 s94, s94, 0
	s_cmp_gt_u32 s95, 13
	s_barrier
	s_cbranch_scc0 .LBB0_713
	s_and_b64 vcc, exec, s[28:29]
	s_cbranch_vccz .LBB0_716
	s_barrier

.LBB0_1200:
	ds_read_b128 v[120:123], v207
	ds_read_b128 v[132:135], v207 offset:1024
	ds_read_b128 v[136:139], v207 offset:2048
	ds_read_b128 v[140:143], v207 offset:3072
	ds_read_b128 v[144:147], v208
	ds_read_b128 v[148:151], v208 offset:1024
	ds_read_b128 v[152:155], v208 offset:2048
	ds_read_b128 v[156:159], v208 offset:3072
	s_add_u32 s34, s28, 0xfffc0080
	s_addc_u32 s35, s29, -1
	s_cmp_eq_u32 s61, 12
	s_cselect_b32 s41, s21, s35
	s_cselect_b32 s40, s57, s34
	s_cselect_b32 s35, s19, s60
	s_cselect_b32 s34, s58, s59
	v_lshl_add_u64 v[222:223], s[28:29], 0, v[190:191]
	s_add_i32 m0, s45, 0xc000
	ds_read_b128 v[160:163], v209
	ds_read_b128 v[164:167], v209 offset:1024
	ds_read_b128 v[168:171], v209 offset:2048
	ds_read_b128 v[172:175], v209 offset:3072
	ds_read_b128 v[176:179], v209 offset:4096
	ds_read_b128 v[210:213], v209 offset:5120
	ds_read_b128 v[214:217], v209 offset:6144
	ds_read_b128 v[218:221], v209 offset:7168
	global_load_lds_dwordx4 v[222:223], off
	v_lshl_add_u64 v[222:223], s[28:29], 0, v[192:193]
	s_add_i32 m0, s45, 0xe000
	s_nop 0
	global_load_lds_dwordx4 v[222:223], off
	s_waitcnt vmcnt(8)
	s_waitcnt lgkmcnt(0)
	s_barrier
	s_setprio 1
	s_waitcnt lgkmcnt(0)
	v_mfma_f32_16x16x32_bf16 v[128:131], v[120:123], v[160:163], v[128:131]
	v_mfma_f32_16x16x32_bf16 v[124:127], v[136:139], v[160:163], v[124:127]
	v_mfma_f32_16x16x32_bf16 v[108:111], v[120:123], v[168:171], v[108:111]
	v_mfma_f32_16x16x32_bf16 v[104:107], v[136:139], v[168:171], v[104:107]
	v_mfma_f32_16x16x32_bf16 v[92:95], v[120:123], v[176:179], v[92:95]
	v_mfma_f32_16x16x32_bf16 v[88:91], v[136:139], v[176:179], v[88:91]
	v_mfma_f32_16x16x32_bf16 v[76:79], v[120:123], v[214:217], v[76:79]
	v_mfma_f32_16x16x32_bf16 v[72:75], v[136:139], v[214:217], v[72:75]
	v_mfma_f32_16x16x32_bf16 v[128:131], v[132:135], v[164:167], v[128:131]
	v_mfma_f32_16x16x32_bf16 v[124:127], v[140:143], v[164:167], v[124:127]
	v_mfma_f32_16x16x32_bf16 v[108:111], v[132:135], v[172:175], v[108:111]
	v_mfma_f32_16x16x32_bf16 v[104:107], v[140:143], v[172:175], v[104:107]
	v_mfma_f32_16x16x32_bf16 v[92:95], v[132:135], v[210:213], v[92:95]
	v_mfma_f32_16x16x32_bf16 v[88:91], v[140:143], v[210:213], v[88:91]
	v_mfma_f32_16x16x32_bf16 v[76:79], v[132:135], v[218:221], v[76:79]
	v_mfma_f32_16x16x32_bf16 v[72:75], v[140:143], v[218:221], v[72:75]
	s_setprio 0
	s_setprio 1
	v_mfma_f32_16x16x32_bf16 v[116:119], v[144:147], v[160:163], v[116:119]
	v_mfma_f32_16x16x32_bf16 v[112:115], v[152:155], v[160:163], v[112:115]
	v_mfma_f32_16x16x32_bf16 v[100:103], v[144:147], v[168:171], v[100:103]
	v_mfma_f32_16x16x32_bf16 v[96:99], v[152:155], v[168:171], v[96:99]
	v_mfma_f32_16x16x32_bf16 v[84:87], v[144:147], v[176:179], v[84:87]
	v_mfma_f32_16x16x32_bf16 v[80:83], v[152:155], v[176:179], v[80:83]
	v_mfma_f32_16x16x32_bf16 v[68:71], v[144:147], v[214:217], v[68:71]
	v_mfma_f32_16x16x32_bf16 v[64:67], v[152:155], v[214:217], v[64:67]
	v_mfma_f32_16x16x32_bf16 v[116:119], v[148:151], v[164:167], v[116:119]
	v_mfma_f32_16x16x32_bf16 v[112:115], v[156:159], v[164:167], v[112:115]
	v_mfma_f32_16x16x32_bf16 v[100:103], v[148:151], v[172:175], v[100:103]
	v_mfma_f32_16x16x32_bf16 v[96:99], v[156:159], v[172:175], v[96:99]
	v_mfma_f32_16x16x32_bf16 v[84:87], v[148:151], v[210:213], v[84:87]
	v_mfma_f32_16x16x32_bf16 v[80:83], v[156:159], v[210:213], v[80:83]
	v_mfma_f32_16x16x32_bf16 v[68:71], v[148:151], v[218:221], v[68:71]
	v_mfma_f32_16x16x32_bf16 v[64:67], v[156:159], v[218:221], v[64:67]
	s_setprio 0
	s_barrier
	ds_read_b128 v[160:163], v209 offset:16384
	ds_read_b128 v[164:167], v209 offset:17408
	ds_read_b128 v[168:171], v209 offset:18432
	ds_read_b128 v[172:175], v209 offset:19456
	ds_read_b128 v[176:179], v209 offset:20480
	ds_read_b128 v[210:213], v209 offset:21504
	ds_read_b128 v[214:217], v209 offset:22528
	ds_read_b128 v[218:221], v209 offset:23552
	s_add_i32 s62, s53, s44
	s_mov_b32 m0, s62
	v_lshl_add_u64 v[222:223], s[34:35], 0, v[182:183]
	global_load_lds_dwordx4 v[222:223], off
	s_add_i32 m0, s62, 0x2000
	s_add_u32 s62, s34, 0x40000
	v_lshl_add_u64 v[224:225], s[34:35], 0, v[186:187]
	s_addc_u32 s63, s35, 0
	s_add_i32 s64, s54, s44
	global_load_lds_dwordx4 v[224:225], off
	v_lshl_add_u64 v[226:227], s[62:63], 0, v[182:183]
	s_mov_b32 m0, s64
	v_lshl_add_u64 v[228:229], s[40:41], 0, v[184:185]
	global_load_lds_dwordx4 v[226:227], off
	v_lshl_add_u64 v[226:227], s[62:63], 0, v[186:187]
	s_add_i32 m0, s64, 0x2000
	s_nop 0
	global_load_lds_dwordx4 v[226:227], off
	v_lshl_add_u64 v[226:227], s[40:41], 0, v[180:181]
	s_mov_b32 m0, s45
	s_nop 0
	global_load_lds_dwordx4 v[226:227], off
	s_mov_b32 m0, s46
	s_nop 0
	global_load_lds_dwordx4 v[228:229], off
	s_waitcnt vmcnt(8)
	s_waitcnt lgkmcnt(0)
	s_barrier
	s_setprio 1
	s_waitcnt lgkmcnt(0)
	v_mfma_f32_16x16x32_bf16 v[60:63], v[120:123], v[160:163], v[60:63]
	v_mfma_f32_16x16x32_bf16 v[56:59], v[136:139], v[160:163], v[56:59]
	v_mfma_f32_16x16x32_bf16 v[44:47], v[120:123], v[168:171], v[44:47]
	v_mfma_f32_16x16x32_bf16 v[40:43], v[136:139], v[168:171], v[40:43]
	v_mfma_f32_16x16x32_bf16 v[28:31], v[120:123], v[176:179], v[28:31]
	v_mfma_f32_16x16x32_bf16 v[24:27], v[136:139], v[176:179], v[24:27]
	v_mfma_f32_16x16x32_bf16 v[12:15], v[120:123], v[214:217], v[12:15]
	v_mfma_f32_16x16x32_bf16 v[8:11], v[136:139], v[214:217], v[8:11]
	v_mfma_f32_16x16x32_bf16 v[60:63], v[132:135], v[164:167], v[60:63]
	v_mfma_f32_16x16x32_bf16 v[56:59], v[140:143], v[164:167], v[56:59]
	v_mfma_f32_16x16x32_bf16 v[44:47], v[132:135], v[172:175], v[44:47]
	v_mfma_f32_16x16x32_bf16 v[40:43], v[140:143], v[172:175], v[40:43]
	v_mfma_f32_16x16x32_bf16 v[28:31], v[132:135], v[210:213], v[28:31]
	v_mfma_f32_16x16x32_bf16 v[24:27], v[140:143], v[210:213], v[24:27]
	v_mfma_f32_16x16x32_bf16 v[12:15], v[132:135], v[218:221], v[12:15]
	v_mfma_f32_16x16x32_bf16 v[8:11], v[140:143], v[218:221], v[8:11]
	s_setprio 0
	s_setprio 1
	v_mfma_f32_16x16x32_bf16 v[52:55], v[144:147], v[160:163], v[52:55]
	v_mfma_f32_16x16x32_bf16 v[48:51], v[152:155], v[160:163], v[48:51]
	v_mfma_f32_16x16x32_bf16 v[36:39], v[144:147], v[168:171], v[36:39]
	v_mfma_f32_16x16x32_bf16 v[32:35], v[152:155], v[168:171], v[32:35]
	v_mfma_f32_16x16x32_bf16 v[20:23], v[144:147], v[176:179], v[20:23]
	v_mfma_f32_16x16x32_bf16 v[16:19], v[152:155], v[176:179], v[16:19]
	v_mfma_f32_16x16x32_bf16 v[4:7], v[144:147], v[214:217], v[4:7]
	v_mfma_f32_16x16x32_bf16 v[0:3], v[152:155], v[214:217], v[0:3]
	v_mfma_f32_16x16x32_bf16 v[52:55], v[148:151], v[164:167], v[52:55]
	v_mfma_f32_16x16x32_bf16 v[48:51], v[156:159], v[164:167], v[48:51]
	v_mfma_f32_16x16x32_bf16 v[36:39], v[148:151], v[172:175], v[36:39]
	v_mfma_f32_16x16x32_bf16 v[32:35], v[156:159], v[172:175], v[32:35]
	v_mfma_f32_16x16x32_bf16 v[20:23], v[148:151], v[210:213], v[20:23]
	v_mfma_f32_16x16x32_bf16 v[16:19], v[156:159], v[210:213], v[16:19]
	v_mfma_f32_16x16x32_bf16 v[4:7], v[148:151], v[218:221], v[4:7]
	v_mfma_f32_16x16x32_bf16 v[0:3], v[156:159], v[218:221], v[0:3]
	s_setprio 0
	s_barrier
	s_add_i32 s62, 0, 0x18000
	s_add_i32 s63, 0, 0x1c000
	v_add_u32_e32 v140, s62, v201
	v_add_u32_e32 v156, s63, v201
	ds_read_b128 v[120:123], v140
	ds_read_b128 v[132:135], v140 offset:1024
	ds_read_b128 v[136:139], v140 offset:2048
	ds_read_b128 v[140:143], v140 offset:3072
	ds_read_b128 v[144:147], v156
	ds_read_b128 v[148:151], v156 offset:1024
	ds_read_b128 v[152:155], v156 offset:2048
	ds_read_b128 v[156:159], v156 offset:3072
	s_add_u32 s40, s40, 0x40000
	s_addc_u32 s41, s41, 0
	s_mov_b32 m0, s47
	v_lshl_add_u64 v[230:231], s[40:41], 0, v[180:181]
	ds_read_b128 v[160:163], v209 offset:32768
	ds_read_b128 v[164:167], v209 offset:33792
	ds_read_b128 v[168:171], v209 offset:34816
	ds_read_b128 v[172:175], v209 offset:35840
	ds_read_b128 v[176:179], v209 offset:36864
	ds_read_b128 v[210:213], v209 offset:37888
	ds_read_b128 v[214:217], v209 offset:38912
	ds_read_b128 v[218:221], v209 offset:39936
	global_load_lds_dwordx4 v[230:231], off
	v_lshl_add_u64 v[230:231], s[40:41], 0, v[184:185]
	s_mov_b32 m0, s48
	s_nop 0
	global_load_lds_dwordx4 v[230:231], off
	s_waitcnt vmcnt(8)
	s_waitcnt lgkmcnt(0)
	s_barrier
	s_setprio 1
	s_waitcnt lgkmcnt(0)
	v_mfma_f32_16x16x32_bf16 v[128:131], v[120:123], v[160:163], v[128:131]
	v_mfma_f32_16x16x32_bf16 v[124:127], v[136:139], v[160:163], v[124:127]
	v_mfma_f32_16x16x32_bf16 v[108:111], v[120:123], v[168:171], v[108:111]
	v_mfma_f32_16x16x32_bf16 v[104:107], v[136:139], v[168:171], v[104:107]
	v_mfma_f32_16x16x32_bf16 v[92:95], v[120:123], v[176:179], v[92:95]
	v_mfma_f32_16x16x32_bf16 v[88:91], v[136:139], v[176:179], v[88:91]
	v_mfma_f32_16x16x32_bf16 v[76:79], v[120:123], v[214:217], v[76:79]
	v_mfma_f32_16x16x32_bf16 v[72:75], v[136:139], v[214:217], v[72:75]
	v_mfma_f32_16x16x32_bf16 v[128:131], v[132:135], v[164:167], v[128:131]
	v_mfma_f32_16x16x32_bf16 v[124:127], v[140:143], v[164:167], v[124:127]
	v_mfma_f32_16x16x32_bf16 v[108:111], v[132:135], v[172:175], v[108:111]
	v_mfma_f32_16x16x32_bf16 v[104:107], v[140:143], v[172:175], v[104:107]
	v_mfma_f32_16x16x32_bf16 v[92:95], v[132:135], v[210:213], v[92:95]
	v_mfma_f32_16x16x32_bf16 v[88:91], v[140:143], v[210:213], v[88:91]
	v_mfma_f32_16x16x32_bf16 v[76:79], v[132:135], v[218:221], v[76:79]
	v_mfma_f32_16x16x32_bf16 v[72:75], v[140:143], v[218:221], v[72:75]
	s_setprio 0
	s_setprio 1
	v_mfma_f32_16x16x32_bf16 v[116:119], v[144:147], v[160:163], v[116:119]
	v_mfma_f32_16x16x32_bf16 v[112:115], v[152:155], v[160:163], v[112:115]
	v_mfma_f32_16x16x32_bf16 v[100:103], v[144:147], v[168:171], v[100:103]
	v_mfma_f32_16x16x32_bf16 v[96:99], v[152:155], v[168:171], v[96:99]
	v_mfma_f32_16x16x32_bf16 v[84:87], v[144:147], v[176:179], v[84:87]
	v_mfma_f32_16x16x32_bf16 v[80:83], v[152:155], v[176:179], v[80:83]
	v_mfma_f32_16x16x32_bf16 v[68:71], v[144:147], v[214:217], v[68:71]
	v_mfma_f32_16x16x32_bf16 v[64:67], v[152:155], v[214:217], v[64:67]
	v_mfma_f32_16x16x32_bf16 v[116:119], v[148:151], v[164:167], v[116:119]
	v_mfma_f32_16x16x32_bf16 v[112:115], v[156:159], v[164:167], v[112:115]
	v_mfma_f32_16x16x32_bf16 v[100:103], v[148:151], v[172:175], v[100:103]
	v_mfma_f32_16x16x32_bf16 v[96:99], v[156:159], v[172:175], v[96:99]
	v_mfma_f32_16x16x32_bf16 v[84:87], v[148:151], v[210:213], v[84:87]
	v_mfma_f32_16x16x32_bf16 v[80:83], v[156:159], v[210:213], v[80:83]
	v_mfma_f32_16x16x32_bf16 v[68:71], v[148:151], v[218:221], v[68:71]
	v_mfma_f32_16x16x32_bf16 v[64:67], v[156:159], v[218:221], v[64:67]
	s_setprio 0
	s_barrier
	ds_read_b128 v[160:163], v209 offset:49152
	ds_read_b128 v[164:167], v209 offset:50176
	ds_read_b128 v[168:171], v209 offset:51200
	ds_read_b128 v[172:175], v209 offset:52224
	ds_read_b128 v[176:179], v209 offset:53248
	ds_read_b128 v[210:213], v209 offset:54272
	ds_read_b128 v[214:217], v209 offset:55296
	ds_read_b128 v[218:221], v209 offset:56320
	s_add_i32 s40, s62, s44
	s_mov_b32 m0, s40
	v_lshl_add_u64 v[222:223], v[222:223], 0, s[12:13]
	global_load_lds_dwordx4 v[222:223], off
	s_add_i32 m0, s40, 0x2000
	s_add_u32 s34, s34, 0x40080
	v_lshl_add_u64 v[222:223], v[224:225], 0, s[12:13]
	s_addc_u32 s35, s35, 0
	s_add_i32 s40, s63, s44
	global_load_lds_dwordx4 v[222:223], off
	v_lshl_add_u64 v[222:223], s[34:35], 0, v[182:183]
	s_mov_b32 m0, s40
	s_nop 0
	global_load_lds_dwordx4 v[222:223], off
	v_lshl_add_u64 v[222:223], s[34:35], 0, v[186:187]
	s_add_i32 m0, s40, 0x2000
	s_nop 0
	global_load_lds_dwordx4 v[222:223], off
	v_lshl_add_u64 v[222:223], v[226:227], 0, s[12:13]
	s_mov_b32 m0, s49
	s_nop 0
	global_load_lds_dwordx4 v[222:223], off
	v_lshl_add_u64 v[222:223], v[228:229], 0, s[12:13]
	s_mov_b32 m0, s50
	s_nop 0
	global_load_lds_dwordx4 v[222:223], off
	s_waitcnt vmcnt(8)
	s_waitcnt lgkmcnt(0)
	s_barrier
	s_setprio 1
	s_waitcnt lgkmcnt(0)
	v_mfma_f32_16x16x32_bf16 v[60:63], v[120:123], v[160:163], v[60:63]
	v_mfma_f32_16x16x32_bf16 v[56:59], v[136:139], v[160:163], v[56:59]
	v_mfma_f32_16x16x32_bf16 v[44:47], v[120:123], v[168:171], v[44:47]
	v_mfma_f32_16x16x32_bf16 v[40:43], v[136:139], v[168:171], v[40:43]
	v_mfma_f32_16x16x32_bf16 v[28:31], v[120:123], v[176:179], v[28:31]
	v_mfma_f32_16x16x32_bf16 v[24:27], v[136:139], v[176:179], v[24:27]
	v_mfma_f32_16x16x32_bf16 v[12:15], v[120:123], v[214:217], v[12:15]
	v_mfma_f32_16x16x32_bf16 v[8:11], v[136:139], v[214:217], v[8:11]
	v_mfma_f32_16x16x32_bf16 v[60:63], v[132:135], v[164:167], v[60:63]
	v_mfma_f32_16x16x32_bf16 v[56:59], v[140:143], v[164:167], v[56:59]
	v_mfma_f32_16x16x32_bf16 v[44:47], v[132:135], v[172:175], v[44:47]
	v_mfma_f32_16x16x32_bf16 v[40:43], v[140:143], v[172:175], v[40:43]
	v_mfma_f32_16x16x32_bf16 v[28:31], v[132:135], v[210:213], v[28:31]
	v_mfma_f32_16x16x32_bf16 v[24:27], v[140:143], v[210:213], v[24:27]
	v_mfma_f32_16x16x32_bf16 v[12:15], v[132:135], v[218:221], v[12:15]
	v_mfma_f32_16x16x32_bf16 v[8:11], v[140:143], v[218:221], v[8:11]
	s_setprio 0
	s_setprio 1
	v_mfma_f32_16x16x32_bf16 v[52:55], v[144:147], v[160:163], v[52:55]
	v_mfma_f32_16x16x32_bf16 v[48:51], v[152:155], v[160:163], v[48:51]
	v_mfma_f32_16x16x32_bf16 v[36:39], v[144:147], v[168:171], v[36:39]
	v_mfma_f32_16x16x32_bf16 v[32:35], v[152:155], v[168:171], v[32:35]
	v_mfma_f32_16x16x32_bf16 v[20:23], v[144:147], v[176:179], v[20:23]
	v_mfma_f32_16x16x32_bf16 v[16:19], v[152:155], v[176:179], v[16:19]
	v_mfma_f32_16x16x32_bf16 v[4:7], v[144:147], v[214:217], v[4:7]
	v_mfma_f32_16x16x32_bf16 v[0:3], v[152:155], v[214:217], v[0:3]
	v_mfma_f32_16x16x32_bf16 v[52:55], v[148:151], v[164:167], v[52:55]
	v_mfma_f32_16x16x32_bf16 v[48:51], v[156:159], v[164:167], v[48:51]
	v_mfma_f32_16x16x32_bf16 v[36:39], v[148:151], v[172:175], v[36:39]
	v_mfma_f32_16x16x32_bf16 v[32:35], v[156:159], v[172:175], v[32:35]
	v_mfma_f32_16x16x32_bf16 v[20:23], v[148:151], v[210:213], v[20:23]
	v_mfma_f32_16x16x32_bf16 v[16:19], v[156:159], v[210:213], v[16:19]
	v_mfma_f32_16x16x32_bf16 v[4:7], v[148:151], v[218:221], v[4:7]
	v_mfma_f32_16x16x32_bf16 v[0:3], v[156:159], v[218:221], v[0:3]
	s_setprio 0
	s_add_i32 s61, s61, 2
	s_add_u32 s28, s28, 0x100
	s_addc_u32 s29, s29, 0
	s_add_u32 s59, s59, 0x100
	s_addc_u32 s60, s60, 0
	s_cmp_gt_u32 s61, 13
	s_barrier
	s_cbranch_scc0 .LBB0_1200
	s_and_b64 vcc, exec, s[14:15]
	s_cbranch_vccz .LBB0_1203
	s_barrier
